# GLA main: wave-uniform score select rewritten as scalar branch (removes 180-instr v_cmp/v_cndmask chain per chunk)
# speedup vs baseline: 1.0097x; 1.0097x over previous
.LBB0_634:
	s_or_b64 exec, exec, s[2:3]
	ds_read_u16 v0, v149 offset:55040
	ds_read_u16 v1, v149 offset:55296
	ds_read_u16 v2, v149 offset:55552
	ds_read_u16 v3, v149 offset:55808
	ds_read_u16 v4, v149 offset:56064
	ds_read_u16 v5, v149 offset:56320
	ds_read_u16 v6, v149 offset:56576
	ds_read_u16 v7, v149 offset:56832
	s_waitcnt lgkmcnt(6)
	v_lshl_or_b32 v0, v1, 16, v0
	s_waitcnt lgkmcnt(4)
	v_lshl_or_b32 v1, v3, 16, v2
	s_waitcnt lgkmcnt(2)
	v_lshl_or_b32 v2, v5, 16, v4
	ds_read_u16 v4, v149 offset:57088
	ds_read_u16 v5, v149 offset:57344
	ds_read_u16 v8, v149 offset:57600
	ds_read_u16 v9, v149 offset:57856
	ds_read_u16 v10, v149 offset:58112
	ds_read_u16 v11, v149 offset:58368
	ds_read_u16 v12, v149 offset:58624
	ds_read_u16 v13, v149 offset:58880
	s_waitcnt lgkmcnt(8)
	v_lshl_or_b32 v3, v7, 16, v6
	s_waitcnt lgkmcnt(6)
	v_lshl_or_b32 v4, v5, 16, v4
	s_waitcnt lgkmcnt(4)
	v_lshl_or_b32 v5, v9, 16, v8
	s_waitcnt lgkmcnt(2)
	v_lshl_or_b32 v6, v11, 16, v10
	s_waitcnt lgkmcnt(0)
	v_lshl_or_b32 v7, v13, 16, v12
	ds_write_b128 v150, v[0:3] offset:14336
	ds_write_b128 v150, v[4:7] offset:14352
	s_waitcnt lgkmcnt(0)
	s_barrier
	ds_read_b128 v[0:3], v151
	ds_read_b128 v[4:7], v151 offset:4608
	ds_read_b128 v[16:19], v151 offset:32
	ds_read_b128 v[20:23], v151 offset:4640
	s_waitcnt lgkmcnt(2)
	v_mfma_f32_32x32x16_bf16 v[0:15], v[0:3], v[4:7], 0
	v_add_u32_e32 v182, v73, v123
	s_add_i32 s43, s10, -1
	s_add_i32 s54, s75, 1
	s_and_b64 s[2:3], s[36:37], exec
	s_cselect_b32 s2, s54, s43
	s_add_i32 s75, s75, -1
	s_waitcnt lgkmcnt(0)
	v_mfma_f32_32x32x16_bf16 v[0:15], v[16:19], v[20:23], v[0:15]
	ds_read_b128 v[16:19], v151 offset:64
	ds_read_b128 v[20:23], v151 offset:4672
	ds_read_b128 v[24:27], v151 offset:96
	ds_read_b128 v[28:31], v151 offset:4704
	s_add_i32 s10, s10, 1
	s_cmp_eq_u32 s75, -2
	s_waitcnt lgkmcnt(2)
	v_mfma_f32_32x32x16_bf16 v[0:15], v[16:19], v[20:23], v[0:15]
	s_waitcnt lgkmcnt(0)
	v_mfma_f32_32x32x16_bf16 v[0:15], v[24:27], v[28:31], v[0:15]
	s_nop 11
	v_cmp_eq_u32_e32 vcc, 0, v108
	s_cbranch_vccnz .Lgsel_w0
	v_cmp_eq_u32_e32 vcc, 4, v108
	s_cbranch_vccnz .Lgsel_w1
	v_cmp_eq_u32_e32 vcc, 8, v108
	s_cbranch_vccnz .Lgsel_w2
	v_cvt_pk_bf16_f32 v16, v12, v12
	v_cvt_pk_bf16_f32 v17, v13, v13
	v_cvt_pk_bf16_f32 v18, v14, v14
	v_cvt_pk_bf16_f32 v19, v15, v15
	s_branch .Lgsel_done
.Lgsel_w0:
	v_cvt_pk_bf16_f32 v16, v0, v0
	v_cvt_pk_bf16_f32 v17, v1, v1
	v_cvt_pk_bf16_f32 v18, v2, v2
	v_cvt_pk_bf16_f32 v19, v3, v3
	s_branch .Lgsel_done
.Lgsel_w1:
	v_cvt_pk_bf16_f32 v16, v4, v4
	v_cvt_pk_bf16_f32 v17, v5, v5
	v_cvt_pk_bf16_f32 v18, v6, v6
	v_cvt_pk_bf16_f32 v19, v7, v7
	s_branch .Lgsel_done
.Lgsel_w2:
	v_cvt_pk_bf16_f32 v16, v8, v8
	v_cvt_pk_bf16_f32 v17, v9, v9
	v_cvt_pk_bf16_f32 v18, v10, v10
	v_cvt_pk_bf16_f32 v19, v11, v11
.Lgsel_done:
	v_cndmask_b32_e64 v16, v16, 0, s[44:45]
	v_cndmask_b32_e64 v17, v17, 0, s[46:47]
	v_cndmask_b32_e64 v18, v18, 0, s[48:49]
	v_cndmask_b32_e64 v19, v19, 0, s[50:51]
	ds_write_b16 v152, v16 offset:24576
	ds_write_b16 v152, v17 offset:24656
	ds_write_b16 v152, v18 offset:24736
	ds_write_b16 v152, v19 offset:24816
	s_waitcnt lgkmcnt(0)
	s_barrier
	ds_read_b128 v[0:3], v154 offset:9216
	ds_read_b128 v[24:27], v153 offset:14336
	ds_read_b128 v[158:161], v153 offset:14368
	ds_read_b128 v[56:59], v151 offset:96
	ds_read_b128 v[4:7], v154 offset:24576
	ds_read_b128 v[28:31], v154 offset:9248
	s_waitcnt lgkmcnt(4)
	v_mfma_f32_32x32x16_bf16 v[8:23], v[0:3], v[24:27], 0
	ds_read_b128 v[162:165], v154 offset:24608
	ds_read_b128 v[166:169], v182 offset:27136
	ds_read_b128 v[64:67], v151 offset:32
	ds_read_b128 v[60:63], v151 offset:64
	ds_read_b128 v[170:173], v151
	ds_read_b128 v[0:3], v126 offset:45568
	s_waitcnt lgkmcnt(6)
	v_mfma_f32_32x32x16_bf16 v[8:23], v[28:31], v[158:161], v[8:23]
	s_waitcnt lgkmcnt(0)
	s_nop 10
	v_pk_fma_f32 v[74:75], v[74:75], v[0:1], v[8:9]
	v_pk_fma_f32 v[76:77], v[76:77], v[2:3], v[10:11]
	v_cvt_pk_bf16_f32 v0, v74, v75
	v_cvt_pk_bf16_f32 v1, v76, v77
	ds_write_b64 v109, v[0:1] offset:27136
	ds_read_b128 v[0:3], v126 offset:45600
	s_waitcnt lgkmcnt(0)
	v_pk_fma_f32 v[78:79], v[78:79], v[0:1], v[12:13]
	v_pk_fma_f32 v[80:81], v[80:81], v[2:3], v[14:15]
	v_cvt_pk_bf16_f32 v0, v78, v79
	v_cvt_pk_bf16_f32 v1, v80, v81
	ds_write_b64 v155, v[0:1] offset:27136
	ds_read_b128 v[28:31], v126 offset:45632
	ds_read_b128 v[68:71], v182 offset:27168
	v_mfma_f32_32x32x16_bf16 v[0:15], v[4:7], v[24:27], 0
	s_waitcnt lgkmcnt(1)
	v_fma_f32 v82, v82, v28, v16
	v_fma_f32 v83, v83, v29, v17
	v_fma_f32 v84, v84, v30, v18
	v_fma_f32 v85, v85, v31, v19
	v_cvt_pk_bf16_f32 v16, v82, v83
	v_cvt_pk_bf16_f32 v17, v84, v85
	ds_write_b64 v156, v[16:17] offset:27136
	ds_read_b128 v[16:19], v126 offset:45664
	v_mfma_f32_32x32x16_bf16 v[0:15], v[162:165], v[158:161], v[0:15]
	s_waitcnt lgkmcnt(0)
	v_fma_f32 v86, v86, v16, v20
	v_fma_f32 v87, v87, v17, v21
	v_fma_f32 v88, v88, v18, v22
	v_fma_f32 v89, v89, v19, v23
	v_cvt_pk_bf16_f32 v16, v86, v87
	v_cvt_pk_bf16_f32 v17, v88, v89
	ds_write_b64 v157, v[16:17] offset:27136
	ds_read_b128 v[16:19], v154 offset:11776
	ds_read_b128 v[162:165], v126 offset:45696
	s_waitcnt lgkmcnt(1)
	v_mfma_f32_32x32x16_bf16 v[16:31], v[16:19], v[24:27], 0
	ds_read_b128 v[174:177], v154 offset:11808
	ds_read_b128 v[178:181], v182 offset:27200
	s_waitcnt lgkmcnt(1)
	v_mfma_f32_32x32x16_bf16 v[16:31], v[174:177], v[158:161], v[16:31]
	v_mfma_f32_32x32x16_bf16 v[0:15], v[170:173], v[166:169], v[0:15]
	s_nop 10
	v_fma_f32 v90, v90, v162, v16
	v_fma_f32 v91, v91, v163, v17
	v_fma_f32 v92, v92, v164, v18
	v_fma_f32 v93, v93, v165, v19
	v_cvt_pk_bf16_f32 v16, v90, v91
	v_cvt_pk_bf16_f32 v17, v92, v93
	ds_write_b64 v109, v[16:17] offset:27200
	ds_read_b128 v[16:19], v126 offset:45728
	s_waitcnt lgkmcnt(0)
	v_pk_fma_f32 v[94:95], v[94:95], v[16:17], v[20:21]
	v_mfma_f32_32x32x16_bf16 v[0:15], v[64:67], v[68:71], v[0:15]
	v_fma_f32 v96, v96, v18, v22
	v_fma_f32 v97, v97, v19, v23
	v_cvt_pk_bf16_f32 v16, v94, v95
	v_cvt_pk_bf16_f32 v17, v96, v97
	ds_write_b64 v109, v[16:17] offset:27216
	ds_read_b128 v[16:19], v126 offset:45760
	ds_read_b128 v[20:23], v182 offset:27232
	s_waitcnt lgkmcnt(1)
	v_pk_fma_f32 v[98:99], v[98:99], v[16:17], v[24:25]
	v_mfma_f32_32x32x16_bf16 v[0:15], v[60:63], v[178:181], v[0:15]
	v_fma_f32 v100, v100, v18, v26
	v_fma_f32 v101, v101, v19, v27
	v_cvt_pk_bf16_f32 v16, v98, v99
	v_cvt_pk_bf16_f32 v17, v100, v101
	ds_write_b64 v109, v[16:17] offset:27232
	ds_read_b128 v[16:19], v126 offset:45792
	s_waitcnt lgkmcnt(0)
	v_pk_fma_f32 v[102:103], v[102:103], v[16:17], v[28:29]
	v_mfma_f32_32x32x16_bf16 v[0:15], v[56:59], v[20:23], v[0:15]
	v_fma_f32 v104, v104, v18, v30
	v_fma_f32 v105, v105, v19, v31
	v_cvt_pk_bf16_f32 v16, v102, v103
	v_cvt_pk_bf16_f32 v17, v104, v105
	ds_write_b64 v109, v[16:17] offset:27248
	v_add_u32_e32 v16, 0xb600, v131
	s_nop 5
	ds_write2_b32 v16, v0, v1 offset0:64 offset1:196
	v_add_u32_e32 v0, 0xba00, v131
	ds_write2_b32 v0, v2, v3 offset0:72 offset1:204
	ds_write_b32 v132, v4 offset:46848
	v_add_u32_e32 v0, 0xc800, v131
	ds_write2_b32 v0, v5, v6 offset0:100 offset1:232
	ds_write_b32 v131, v7 offset:52656
	ds_write_b32 v133, v8 offset:46848
	v_add_u32_e32 v0, 0xda00, v131
	ds_write2_b32 v0, v9, v10 offset0:4 offset1:136
	ds_write_b32 v131, v11 offset:56880
	ds_write_b32 v134, v12 offset:46848
	v_add_u32_e32 v0, 0xea00, v131
	ds_write2_b32 v0, v13, v14 offset0:36 offset1:168
	ds_write_b32 v131, v15 offset:61104
	s_waitcnt lgkmcnt(0)
	s_barrier
	v_lshl_add_u32 v16, s2, 5, v127
	ds_read_b128 v[0:3], v128 offset:46848
	ds_read_b128 v[4:7], v128 offset:46864
	ds_read_b128 v[8:11], v128 offset:46880
	ds_read_b128 v[12:15], v128 offset:46896
	v_ashrrev_i32_e32 v17, 31, v16
	v_lshl_add_u64 v[16:17], v[16:17], 0, s[12:13]
	v_lshlrev_b64 v[16:17], 10, v[16:17]
	v_lshl_add_u64 v[16:17], v[118:119], 0, v[16:17]
	s_waitcnt lgkmcnt(3)
	v_cvt_pk_bf16_f32 v0, v0, v1
	v_cvt_pk_bf16_f32 v1, v2, v3
	s_waitcnt lgkmcnt(2)
	v_cvt_pk_bf16_f32 v2, v4, v5
	v_cvt_pk_bf16_f32 v3, v6, v7
	global_store_dwordx4 v[16:17], v[0:3], off
	s_waitcnt lgkmcnt(1)
	s_nop 0
	v_cvt_pk_bf16_f32 v0, v8, v9
	v_cvt_pk_bf16_f32 v1, v10, v11
	s_waitcnt lgkmcnt(0)
	v_cvt_pk_bf16_f32 v2, v12, v13
	v_cvt_pk_bf16_f32 v3, v14, v15
	global_store_dwordx4 v[16:17], v[0:3], off offset:16
	s_cbranch_scc1 .LBB0_643
